# attention zero-reference fast path with threshold 16 (deferred rescale threshold 16 too)
# speedup vs baseline: 1.0095x; 1.0095x over previous
.LBB0_189:
	s_cmp_gt_i32 s27, 1
	s_mov_b64 s[6:7], -1
	s_cbranch_scc0 .LBB0_345
	s_cmp_gt_i32 s27, 2
	s_cbranch_scc0 .LBB0_233
	s_cmp_lt_i32 s94, 19
	s_cbranch_scc1 .LBB0_232
	v_writelane_b32 v255, s27, 36
	s_mov_b32 s4, s18
	v_writelane_b32 v255, s4, 34
	s_add_i32 s8, s18, -2
	v_bfe_u32 v198, v168, 5, 1
	v_writelane_b32 v255, s5, 35
	s_lshl_b32 s4, s8, 1
	s_lshl_b64 s[6:7], s[4:5], 2
	s_add_u32 s6, s88, s6
	s_addc_u32 s7, s89, s7
	global_load_dwordx2 v[170:171], v161, s[6:7] offset:64
	s_lshl_b32 s4, s8, 4
	s_lshl_b64 s[6:7], s[4:5], 2
	s_add_u32 s6, s88, s6
	s_addc_u32 s7, s89, s7
	v_writelane_b32 v255, s6, 37
	v_readlane_b32 s4, v253, 14
	v_readlane_b32 s12, v252, 19
	v_writelane_b32 v255, s7, 38
	v_ashrrev_i32_e32 v200, 4, v166
	v_readlane_b32 s6, v255, 29
	s_cmp_lt_i32 s6, s4
	s_cselect_b64 s[84:85], -1, 0
	s_cmp_ge_i32 s6, s4
	s_cselect_b64 s[6:7], -1, 0
	s_lshl_b32 s4, s8, 7
	s_lshl_b64 s[8:9], s[4:5], 2
	v_and_b32_e32 v4, 15, v168
	v_lshlrev_b32_e32 v5, 4, v168
	v_readlane_b32 s10, v252, 42
	s_movk_i32 s4, 0x110
	v_lshlrev_b32_e32 v160, 4, v198
	v_readlane_b32 s22, v252, 29
	s_waitcnt lgkmcnt(0)
	v_and_b32_e32 v1, 63, v168
	v_ashrrev_i32_e32 v2, 8, v166
	v_lshlrev_b32_e32 v0, 3, v4
	v_and_b32_e32 v174, 0x70, v5
	v_mov_b32_e32 v175, v161
	v_readlane_b32 s11, v252, 43
	v_lshlrev_b32_e32 v4, 4, v4
	v_mul_lo_u32 v6, v200, s4
	v_lshlrev_b32_e32 v201, 3, v168
	v_add_u32_e32 v202, 0, v160
	v_xor_b32_e32 v8, 32, v220
	v_readlane_b32 s20, v252, 27
	v_readlane_b32 s21, v252, 28
	v_readlane_b32 s23, v252, 30
	s_add_u32 s8, s22, s8
	v_and_b32_e32 v181, 31, v168
	v_bfe_u32 v3, v166, 6, 2
	v_lshlrev_b32_e32 v176, 6, v2
	v_ashrrev_i32_e32 v178, 3, v166
	v_lshl_add_u64 v[182:183], s[10:11], 0, v[174:175]
	v_add3_u32 v175, 0, v4, v6
	v_and_b32_e32 v4, 0x60, v5
	v_and_b32_e32 v5, 8, v201
	s_movk_i32 s4, 0x90
	v_lshl_add_u32 v203, v2, 7, v202
	v_readlane_b32 s10, v254, 41
	v_mov_b32_e32 v7, 0x3600
	v_cmp_lt_i32_e32 vcc, v8, v221
	v_cmp_eq_u32_e64 s[38:39], 1, v2
	v_lshl_add_u32 v1, v1, 2, 0
	v_lshlrev_b32_e32 v2, 8, v166
	v_readlane_b32 s20, v255, 17
	s_addc_u32 s9, s23, s9
	v_lshlrev_b32_e32 v199, 5, v3
	v_lshlrev_b32_e32 v172, 3, v198
	v_add3_u32 v6, 0, v4, v5
	v_mul_lo_u32 v167, v178, s4
	v_add3_u32 v4, s10, v4, v5
	v_add_u32_e32 v5, s10, v160
	v_mul_u32_u24_e32 v169, 0x90, v181
	v_mad_u32_u24 v7, v181, s4, v7
	v_cndmask_b32_e32 v8, v220, v8, vcc
	v_lshl_add_u32 v205, v3, 14, v1
	s_movk_i32 s4, 0x100
	v_and_b32_e32 v3, 0xc000, v2
	v_or_b32_e32 v2, 0x3f00, v2
	v_cmp_eq_u32_e64 s[36:37], 0, v166
	v_readlane_b32 s21, v255, 18
	v_ashrrev_i32_e32 v177, 31, v176
	v_ashrrev_i32_e32 v179, 31, v178
	v_mul_u32_u24_e32 v204, 0x110, v181
	v_lshlrev_b32_e32 v180, 2, v198
	v_lshlrev_b32_e32 v173, 2, v8
	v_cmp_gt_u32_e64 s[40:41], s4, v166
	v_add_u32_e32 v206, v1, v3
	v_lshl_add_u64 v[184:185], s[8:9], 0, v[160:161]
	s_mov_b64 s[8:9], -1
	s_waitcnt vmcnt(0)
	v_mov_b32_e32 v186, v170
	v_mov_b32_e32 v187, v170
	v_add_u32_e32 v207, v202, v7
	v_add_u32_e32 v208, v4, v167
	v_add_u32_e32 v209, v5, v169
	v_add_u32_e32 v210, v1, v2
	v_lshlrev_b32_e32 v188, 1, v172
	v_lshlrev_b32_e32 v190, 1, v0
	v_add_u32_e32 v211, v6, v167
	v_readlane_b32 s13, v252, 20
	v_readlane_b32 s14, v252, 21
	v_readlane_b32 s15, v252, 22
	v_readlane_b32 s16, v252, 23
	v_readlane_b32 s17, v252, 24
	v_readlane_b32 s18, v252, 25
	v_readlane_b32 s19, v252, 26
	v_readlane_b32 s24, v252, 31
	v_readlane_b32 s25, v252, 32
	v_readlane_b32 s26, v252, 33
	v_readlane_b32 s27, v252, 34
	s_mov_b32 s98, 0x41800000
	s_branch .LBB0_194

.LBB0_210:
	s_or_b64 exec, exec, s[10:11]
	v_max3_f32 v162, v64, s96, v65
	v_max3_f32 v162, v162, v66, v67
	v_max3_f32 v162, v162, v68, v69
	v_max3_f32 v162, v162, v70, v71
	v_max3_f32 v162, v162, v72, v73
	v_max3_f32 v162, v162, v74, v75
	v_max3_f32 v162, v162, v76, v77
	v_max3_f32 v162, v162, v78, v79
	v_max3_f32 v162, v162, v80, v81
	v_max3_f32 v162, v162, v82, v83
	v_max3_f32 v162, v162, v84, v85
	v_max3_f32 v162, v162, v86, v87
	v_max3_f32 v162, v162, v88, v89
	v_max3_f32 v162, v162, v90, v91
	v_max3_f32 v162, v162, v92, v93
	v_max3_f32 v162, v162, v94, v95
	v_mov_b32_e32 v163, v162
	s_nop 1
	v_permlane32_swap_b32_e32 v162, v163
	v_max_f32_e32 v162, v162, v163
	v_sub_f32_e32 v163, v162, v170
	v_cmp_lt_f32_e32 vcc, 0x41800000, v163
	s_cbranch_vccnz .Lda_upd0
	v_mov_b32_e32 v234, v170
	v_mov_b32_e32 v170, 1.0
	s_branch .LBB0_212

.LBB0_218:
	s_or_b64 exec, exec, s[8:9]
	v_max3_f32 v162, v96, s96, v97
	v_max3_f32 v162, v162, v98, v99
	v_max3_f32 v162, v162, v100, v101
	v_max3_f32 v162, v162, v102, v103
	v_max3_f32 v162, v162, v104, v105
	v_max3_f32 v162, v162, v106, v107
	v_max3_f32 v162, v162, v108, v109
	v_max3_f32 v162, v162, v110, v111
	v_max3_f32 v162, v162, v112, v113
	v_max3_f32 v162, v162, v114, v115
	v_max3_f32 v162, v162, v116, v117
	v_max3_f32 v162, v162, v118, v119
	v_max3_f32 v162, v162, v120, v121
	v_max3_f32 v162, v162, v122, v123
	v_max3_f32 v162, v162, v124, v125
	v_max3_f32 v162, v162, v126, v127
	v_mov_b32_e32 v163, v162
	s_nop 1
	v_permlane32_swap_b32_e32 v162, v163
	v_max_f32_e32 v162, v162, v163
	v_sub_f32_e32 v163, v162, v170
	v_cmp_lt_f32_e32 vcc, 0x41800000, v163
	s_cbranch_vccnz .Lda_upd1
	v_mov_b32_e32 v234, v170
	v_mov_b32_e32 v170, 1.0
	s_branch .LBB0_203
